# ring4+R4 + all 12 K/Q LDS reads issued up-front into distinct registers (counted lgkmcnt)
# baseline (speedup 1.0000x reference)
.LBB0_398:
	ds_read_b128 v[64:67], v208 offset:40960
	ds_read_b128 v[68:71], v204 offset:51200
	ds_read_b128 v[222:225], v209 offset:40960
	ds_read_b128 v[72:75], v204 offset:52224
	ds_read_b128 v[230:233], v210 offset:40960
	ds_read_b128 v[186:189], v204 offset:53248
	ds_read_b128 v[234:237], v211 offset:40960
	ds_read_b128 v[214:217], v204 offset:54272
	ds_read_b128 v[76:79], v208 offset:45056
	ds_read_b128 v[182:185], v209 offset:45056
	ds_read_b128 v[226:229], v210 offset:45056
	ds_read_b128 v[218:221], v211 offset:45056
	v_exp_f32_e32 v148, v80
	v_exp_f32_e32 v149, v81
	s_waitcnt lgkmcnt(10)
	v_mfma_f32_32x32x16_bf16 v[112:127], v[64:67], v[68:71], v[96:111]
	v_exp_f32_e32 v154, v84
	v_exp_f32_e32 v155, v85
	v_exp_f32_e32 v158, v86
	v_exp_f32_e32 v159, v87
	v_exp_f32_e32 v156, v90
	v_exp_f32_e32 v157, v91
	s_waitcnt lgkmcnt(8)
	v_mfma_f32_32x32x16_bf16 v[112:127], v[222:225], v[72:75], v[112:127]
	v_exp_f32_e32 v166, v94
	v_exp_f32_e32 v167, v95
	s_waitcnt lgkmcnt(6)
	v_mfma_f32_32x32x16_bf16 v[112:127], v[230:233], v[186:189], v[112:127]
	v_exp_f32_e32 v152, v82
	v_exp_f32_e32 v153, v83
	v_exp_f32_e32 v150, v88
	v_exp_f32_e32 v151, v89
	s_waitcnt lgkmcnt(4)
	v_mfma_f32_32x32x16_bf16 v[112:127], v[234:237], v[214:217], v[112:127]
	v_exp_f32_e32 v162, v92
	v_exp_f32_e32 v163, v93
	s_waitcnt lgkmcnt(3)
	v_mfma_f32_32x32x16_bf16 v[80:95], v[76:79], v[68:71], v[96:111]
	v_add_f32_e32 v68, v164, v148
	v_add_f32_e32 v68, v149, v68
	v_add_f32_e32 v68, v152, v68
	v_add_f32_e32 v68, v153, v68
	v_add_f32_e32 v68, v154, v68
	v_add_f32_e32 v68, v155, v68
	v_add_f32_e32 v68, v158, v68
	s_waitcnt lgkmcnt(2)
	v_mfma_f32_32x32x16_bf16 v[80:95], v[182:185], v[72:75], v[80:95]
	v_add_f32_e32 v68, v159, v68
	v_add_f32_e32 v68, v150, v68
	v_add_f32_e32 v68, v151, v68
	v_add_f32_e32 v68, v156, v68
	v_add_f32_e32 v68, v157, v68
	v_add_f32_e32 v68, v162, v68
	v_add_f32_e32 v68, v163, v68
	s_waitcnt lgkmcnt(1)
	v_mfma_f32_32x32x16_bf16 v[80:95], v[226:229], v[186:189], v[80:95]
	v_add_f32_e32 v64, v166, v68
	v_add_f32_e32 v64, v167, v64
	v_mov_b32_e32 v65, v64
	s_nop 1
	v_permlane32_swap_b32_e32 v64, v65
	v_add_f32_e32 v164, v64, v65
	v_cmp_ge_f32_e32 vcc, s99, v164
	s_waitcnt lgkmcnt(0)
	v_mfma_f32_32x32x16_bf16 v[80:95], v[218:221], v[214:217], v[80:95]
	s_cmp_eq_u64 vcc, exec
	s_cbranch_scc0 .LBB0_405
.LBB0_400:
	v_cvt_pk_bf16_f32 v182, v148, v149
	v_cvt_pk_bf16_f32 v183, v152, v153
	v_cvt_pk_bf16_f32 v184, v154, v155
	v_cvt_pk_bf16_f32 v185, v158, v159
	v_cvt_pk_bf16_f32 v160, v150, v151
	v_cvt_pk_bf16_f32 v161, v156, v157
	v_cvt_pk_bf16_f32 v162, v162, v163
	v_cvt_pk_bf16_f32 v163, v166, v167
	s_waitcnt vmcnt(0)
	ds_write_b128 v205, v[132:135]
	ds_write_b128 v206, v[136:139]
	ds_write_b128 v207, v[128:131] offset:32768
	s_cmpk_lt_u32 s51, 0x100
	s_cselect_b32 s0, s38, s34
	s_add_i32 s3, s0, s51
	s_mul_i32 s0, s3, 0x1800
	s_mul_hi_i32 s1, s3, 0x1800
	s_add_u32 s0, s39, s0
	s_addc_u32 s1, s42, s1
	v_lshl_add_u64 v[148:149], s[0:1], 0, v[170:171]
	v_add_co_u32_e32 v152, vcc, s33, v148
	v_mad_i64_i32 v[156:157], s[0:1], s3, v195, v[180:181]
	s_nop 0
	v_addc_co_u32_e32 v153, vcc, 0, v149, vcc
	global_load_dwordx4 v[148:151], v[148:149], off
	s_nop 0
	global_load_dwordx4 v[152:155], v[152:153], off
	s_nop 0
	global_load_dwordx4 v[156:159], v[156:157], off
	ds_read_b64_tr_b16 v[186:187], v203 offset:0
	ds_read_b64_tr_b16 v[188:189], v203 offset:0x800
	ds_read_b64_tr_b16 v[214:215], v203 offset:0x200
	ds_read_b64_tr_b16 v[216:217], v203 offset:0xa00
	ds_read_b64_tr_b16 v[218:219], v203 offset:0x400
	ds_read_b64_tr_b16 v[220:221], v203 offset:0xc00
	ds_read_b64_tr_b16 v[222:223], v203 offset:0x600
	ds_read_b64_tr_b16 v[224:225], v203 offset:0xe00
	ds_read_b64_tr_b16 v[226:227], v203 offset:0x1000
	ds_read_b64_tr_b16 v[228:229], v203 offset:0x1800
	ds_read_b64_tr_b16 v[230:231], v203 offset:0x1200
	ds_read_b64_tr_b16 v[232:233], v203 offset:0x1a00
	ds_read_b64_tr_b16 v[234:235], v203 offset:0x1400
	ds_read_b64_tr_b16 v[236:237], v203 offset:0x1c00
	ds_read_b64_tr_b16 v[238:239], v203 offset:0x1600
	ds_read_b64_tr_b16 v[240:241], v203 offset:0x1e00
	s_nop 0
	s_waitcnt lgkmcnt(8)
	v_exp_f32_e32 v112, v112
	v_mfma_f32_32x32x16_bf16 v[0:15], v[144:147], v[186:189], v[0:15]
	v_exp_f32_e32 v113, v113
	v_exp_f32_e32 v114, v114
	v_exp_f32_e32 v115, v115
	v_exp_f32_e32 v116, v116
	v_exp_f32_e32 v117, v117
	v_exp_f32_e32 v118, v118
	v_exp_f32_e32 v119, v119
	v_mfma_f32_32x32x16_bf16 v[48:63], v[144:147], v[214:217], v[48:63]
	v_exp_f32_e32 v120, v120
	v_exp_f32_e32 v121, v121
	v_exp_f32_e32 v122, v122
	v_exp_f32_e32 v123, v123
	v_exp_f32_e32 v124, v124
	v_exp_f32_e32 v125, v125
	v_exp_f32_e32 v126, v126
	v_mfma_f32_32x32x16_bf16 v[32:47], v[144:147], v[218:221], v[32:47]
	v_exp_f32_e32 v127, v127
	v_mfma_f32_32x32x16_bf16 v[16:31], v[144:147], v[222:225], v[16:31]
	ds_read_b64_tr_b16 v[144:145], v203 offset:0x2000
	ds_read_b64_tr_b16 v[146:147], v203 offset:0x2800
	ds_read_b64_tr_b16 v[186:187], v203 offset:0x2200
	ds_read_b64_tr_b16 v[188:189], v203 offset:0x2a00
	ds_read_b64_tr_b16 v[214:215], v203 offset:0x2400
	ds_read_b64_tr_b16 v[216:217], v203 offset:0x2c00
	ds_read_b64_tr_b16 v[218:219], v203 offset:0x2600
	ds_read_b64_tr_b16 v[220:221], v203 offset:0x2e00
	s_waitcnt lgkmcnt(8)
	ds_read_b64_tr_b16 v[222:223], v203 offset:0x3000
	ds_read_b64_tr_b16 v[224:225], v203 offset:0x3800
	s_nop 0
	v_mfma_f32_32x32x16_bf16 v[0:15], v[140:143], v[226:229], v[0:15]
	ds_read_b64_tr_b16 v[226:227], v203 offset:0x3200
	ds_read_b64_tr_b16 v[228:229], v203 offset:0x3a00
	v_mfma_f32_32x32x16_bf16 v[48:63], v[140:143], v[230:233], v[48:63]
	ds_read_b64_tr_b16 v[230:231], v203 offset:0x3400
	ds_read_b64_tr_b16 v[232:233], v203 offset:0x3c00
	v_mfma_f32_32x32x16_bf16 v[32:47], v[140:143], v[234:237], v[32:47]
	ds_read_b64_tr_b16 v[234:235], v203 offset:0x3600
	ds_read_b64_tr_b16 v[236:237], v203 offset:0x3e00
	s_waitcnt lgkmcnt(8)
	s_nop 0
	s_waitcnt lgkmcnt(0)
	v_mfma_f32_32x32x16_bf16 v[16:31], v[140:143], v[238:241], v[16:31]
	v_add_f32_e32 v140, 0, v112
	v_add_f32_e32 v140, v113, v140
	v_add_f32_e32 v140, v114, v140
	v_add_f32_e32 v140, v115, v140
	v_add_f32_e32 v140, v116, v140
	v_add_f32_e32 v140, v117, v140
	v_add_f32_e32 v140, v118, v140
	v_mfma_f32_32x32x16_bf16 v[0:15], v[182:185], v[144:147], v[0:15]
	v_add_f32_e32 v140, v119, v140
	v_add_f32_e32 v140, v120, v140
	v_add_f32_e32 v140, v121, v140
	v_add_f32_e32 v140, v122, v140
	v_add_f32_e32 v140, v123, v140
	v_add_f32_e32 v140, v124, v140
	v_add_f32_e32 v140, v125, v140
	v_mfma_f32_32x32x16_bf16 v[48:63], v[182:185], v[186:189], v[48:63]
	v_add_f32_e32 v140, v126, v140
	v_add_f32_e32 v165, v127, v140
	v_cvt_pk_bf16_f32 v144, v112, v113
	v_cvt_pk_bf16_f32 v145, v114, v115
	v_cvt_pk_bf16_f32 v146, v116, v117
	v_cvt_pk_bf16_f32 v147, v118, v119
	v_cvt_pk_bf16_f32 v140, v120, v121
	v_mfma_f32_32x32x16_bf16 v[32:47], v[182:185], v[214:217], v[32:47]
	v_cvt_pk_bf16_f32 v141, v122, v123
	v_cvt_pk_bf16_f32 v142, v124, v125
	v_cvt_pk_bf16_f32 v143, v126, v127
	v_mfma_f32_32x32x16_bf16 v[16:31], v[182:185], v[218:221], v[16:31]
	s_waitcnt lgkmcnt(0)
	s_barrier
	v_mfma_f32_32x32x16_bf16 v[0:15], v[160:163], v[222:225], v[0:15]
	v_mfma_f32_32x32x16_bf16 v[48:63], v[160:163], v[226:229], v[48:63]
	v_mfma_f32_32x32x16_bf16 v[32:47], v[160:163], v[230:233], v[32:47]
	v_mfma_f32_32x32x16_bf16 v[16:31], v[160:163], v[234:237], v[16:31]
	v_add_u32_e32 v208, s101, v208
	v_add_u32_e32 v209, s101, v209
	v_add_u32_e32 v210, s101, v210
	v_add_u32_e32 v211, s101, v211
	ds_read_b128 v[64:67], v208 offset:32768
	ds_read_b128 v[214:217], v204 offset:51200
	ds_read_b128 v[68:71], v209 offset:32768
	ds_read_b128 v[218:221], v204 offset:52224
	ds_read_b128 v[72:75], v210 offset:32768
	ds_read_b128 v[230:233], v204 offset:53248
	ds_read_b128 v[76:79], v211 offset:32768
	ds_read_b128 v[234:237], v204 offset:54272
	ds_read_b128 v[222:225], v208 offset:36864
	ds_read_b128 v[226:229], v209 offset:36864
	ds_read_b128 v[238:241], v210 offset:36864
	ds_read_b128 v[242:245], v211 offset:36864
	v_exp_f32_e32 v166, v84
	v_exp_f32_e32 v167, v85
	s_waitcnt lgkmcnt(10)
	v_mfma_f32_32x32x16_bf16 v[112:127], v[64:67], v[214:217], v[96:111]
	v_exp_f32_e32 v186, v90
	v_exp_f32_e32 v187, v91
	s_andn2_b64 s[0:1], s[6:7], exec
	s_and_b64 s[6:7], s[8:9], exec
	s_or_b64 s[6:7], s[0:1], s[6:7]
	s_waitcnt lgkmcnt(8)
	v_mfma_f32_32x32x16_bf16 v[112:127], v[68:71], v[218:221], v[112:127]
	v_exp_f32_e32 v160, v80
	v_exp_f32_e32 v161, v81
	v_exp_f32_e32 v162, v82
	v_exp_f32_e32 v163, v83
	v_add_f32_e32 v80, v160, v165
	v_add_f32_e32 v80, v161, v80
	v_add_f32_e32 v165, v162, v80
	s_waitcnt lgkmcnt(6)
	v_mfma_f32_32x32x16_bf16 v[112:127], v[72:75], v[230:233], v[112:127]
	v_exp_f32_e32 v182, v86
	v_exp_f32_e32 v183, v87
	v_exp_f32_e32 v184, v88
	v_exp_f32_e32 v185, v89
	v_add_f32_e32 v165, v163, v165
	v_add_f32_e32 v165, v166, v165
	v_add_f32_e32 v165, v167, v165
	s_waitcnt lgkmcnt(4)
	v_mfma_f32_32x32x16_bf16 v[112:127], v[76:79], v[234:237], v[112:127]
	v_exp_f32_e32 v188, v92
	v_exp_f32_e32 v189, v93
	v_exp_f32_e32 v190, v94
	v_exp_f32_e32 v191, v95
	v_add_f32_e32 v165, v182, v165
	v_add_f32_e32 v165, v183, v165
	v_add_f32_e32 v165, v184, v165
	s_waitcnt lgkmcnt(3)
	v_mfma_f32_32x32x16_bf16 v[80:95], v[222:225], v[214:217], v[96:111]
	v_add_f32_e32 v165, v185, v165
	v_add_f32_e32 v165, v186, v165
	v_add_f32_e32 v165, v187, v165
	v_add_f32_e32 v165, v188, v165
	v_add_f32_e32 v165, v189, v165
	v_add_f32_e32 v165, v190, v165
	v_add_f32_e32 v165, v191, v165
	s_waitcnt lgkmcnt(2)
	v_mfma_f32_32x32x16_bf16 v[80:95], v[226:229], v[218:221], v[80:95]
	v_mov_b32_e32 v179, v165
	s_nop 1
	v_permlane32_swap_b32_e32 v165, v179
	v_add_f32_e64 v178, v164, v178
	v_add_f32_e64 v179, v165, v179
	v_cmp_ge_f32_e32 vcc, s99, v179
	s_cmp_eq_u64 vcc, exec
	s_waitcnt lgkmcnt(1)
	v_mfma_f32_32x32x16_bf16 v[80:95], v[238:241], v[230:233], v[80:95]
	s_waitcnt lgkmcnt(0)
	v_mfma_f32_32x32x16_bf16 v[80:95], v[242:245], v[234:237], v[80:95]
	s_cbranch_scc0 .LBB0_408
